# GEMM2/5 skew 7.5 us instead of 5 us (tuning by paired measure)
# baseline (speedup 1.0000x reference)
.LBB0_623:
	s_cmp_lt_i32 s64, 5
	s_cselect_b64 s[8:9], -1, 0
	s_and_b64 s[0:1], s[8:9], s[0:1]
	s_cmpk_lt_i32 s2, 0x300
	s_cselect_b64 s[6:7], -1, 0
	s_and_b64 s[0:1], s[0:1], s[6:7]
	s_andn2_b64 vcc, exec, s[0:1]
	s_cbranch_vccnz .LBB0_632
	s_and_b32 s0, s62, 7
	s_cmp_lg_u32 s0, 0
	s_cselect_b64 s[0:1], -1, 0
	s_ashr_i32 s18, s62, 3
	s_add_u32 s19, s96, 0x720000
	s_addc_u32 s20, s97, 0
	s_add_u32 s21, s96, 0x13a0000
	s_addc_u32 s22, s97, 0
	s_add_u32 s10, s96, 0x43a0000
	s_addc_u32 s11, s97, 0
	s_add_u32 s23, s96, 0xecc4000
	s_addc_u32 s24, s97, 0
	s_abs_i32 s25, s62
	v_cvt_f32_u32_e32 v2, s25
	v_cndmask_b32_e64 v1, 0, 1, s[0:1]
	s_sub_i32 s0, 0, s25
	s_mov_b64 s[12:13], s[36:37]
	v_rcp_iflag_f32_e32 v2, v2
	v_mbcnt_hi_u32_b32 v89, -1, v213
	s_lshl_b32 s28, s62, 3
	s_mov_b64 s[14:15], s[38:39]
	v_mul_f32_e32 v2, 0x4f7ffffe, v2
	v_cvt_u32_f32_e32 v2, v2
	s_ashr_i32 s26, s62, 31
	s_sub_i32 s27, 0, s62
	s_lshl_b32 s29, s2, 3
	v_readfirstlane_b32 s1, v2
	s_mul_i32 s0, s0, s1
	s_mul_hi_u32 s0, s1, s0
	v_and_b32_e32 v2, 64, v89
	s_sub_i32 s30, 0, s28
	s_add_i32 s31, s1, s0
	v_cmp_ne_u32_e64 s[0:1], 1, v1
	v_mov_b32_e32 v67, 0
	s_movk_i32 s34, 0x90
	s_mov_b32 s35, 0xfffffc0
	s_mov_b32 s36, 0x20000
	s_mov_b32 s37, 0x40000
	s_mov_b32 s38, 0x60000
	s_movk_i32 s39, 0xff00
	s_movk_i32 s40, 0x410
	s_movk_i32 s41, 0x2000
	v_mov_b32_e32 v1, s15
	v_mov_b32_e32 v86, s13
	v_mov_b32_e32 v87, s14
	v_mov_b32_e32 v88, s12
	s_movk_i32 s42, 0x1000
	v_add_u32_e32 v90, 64, v2
	v_xor_b32_e32 v91, 32, v89
	v_xor_b32_e32 v92, 16, v89
	v_xor_b32_e32 v93, 8, v89
	v_xor_b32_e32 v94, 4, v89
	v_xor_b32_e32 v95, 2, v89
	v_xor_b32_e32 v96, 1, v89
	s_bitcmp1_b32 s2, 3
	s_cbranch_scc0 .Lskew_done_g2
	s_memrealtime s[98:99]
	s_waitcnt lgkmcnt(0)
	s_add_u32 s100, s98, 750

.LBB0_877:
	s_cmp_lt_i32 s64, 10
	s_cselect_b64 s[4:5], -1, 0
	s_and_b64 s[0:1], s[4:5], s[0:1]
	s_and_b64 s[0:1], s[0:1], s[6:7]
	s_andn2_b64 vcc, exec, s[0:1]
	s_cbranch_vccnz .LBB0_884
	s_and_b32 s0, s62, 7
	s_cmp_lg_u32 s0, 0
	s_cselect_b64 s[0:1], -1, 0
	s_ashr_i32 s3, s62, 3
	s_add_u32 s8, s96, 0xda0000
	s_addc_u32 s9, s97, 0
	s_add_u32 s10, s96, 0x13a0000
	s_addc_u32 s11, s97, 0
	s_abs_i32 s12, s62
	v_cvt_f32_u32_e32 v1, s12
	v_cndmask_b32_e64 v0, 0, 1, s[0:1]
	s_sub_i32 s0, 0, s12
	s_lshl_b32 s15, s62, 3
	v_rcp_iflag_f32_e32 v1, v1
	s_ashr_i32 s13, s62, 31
	s_sub_i32 s14, 0, s62
	s_lshl_b32 s16, s2, 3
	v_mul_f32_e32 v1, 0x4f7ffffe, v1
	v_cvt_u32_f32_e32 v1, v1
	s_sub_i32 s17, 0, s15
	v_mov_b32_e32 v65, 0
	s_movk_i32 s19, 0x90
	v_readfirstlane_b32 s1, v1
	s_mul_i32 s0, s0, s1
	s_mul_hi_u32 s0, s1, s0
	s_add_i32 s18, s1, s0
	v_cmp_ne_u32_e64 s[0:1], 1, v0
	s_mov_b32 s20, 0xfffffc0
	s_mov_b32 s21, 0x20000
	s_mov_b32 s22, 0x40000
	s_mov_b32 s23, 0x60000
	s_movk_i32 s24, 0xff00
	s_movk_i32 s25, 0x410
	s_movk_i32 s26, 0x2000
	s_bitcmp1_b32 s2, 3
	s_cbranch_scc0 .Lskew_done_g5
	s_memrealtime s[98:99]
	s_waitcnt lgkmcnt(0)
	s_add_u32 s100, s98, 750
